# K tile LDS swizzle widened from 3 to 4 XOR bits (conflict-free ds_read_b128 groups) on top of v1
# baseline (speedup 1.0000x reference)
; __device__ __forceinline__ int v_rd_base(int lane) { return ((lane & 3) << 3) | (((lane >> 2) & 3) << 6) | (((lane >> 4) & 1) << 5) | (((lane >> 5) & 1) << 8); }
; #define NPUB() do { asm volatile("s_waitcnt vmcnt(0)" ::: "memory"); __syncthreads(); } while (0)
; template <bool NA> __device__ __forceinline__ void unit_body_v128(const Unit& U, char* lds) {
;   int tid = threadIdx.x; asm volatile("" : "+v"(tid)); const int wid = __builtin_amdgcn_readfirstlane(tid >> 6), lane = tid & 63, r32 = lane & 31, hi = lane >> 5;
;   char* V_lds = lds; char* K_lds = lds + 2 * DA_VB;
;   float* ws = (float*)(lds + DA_WS_OFF) + wid * 64; float* li_l = ws; float* al_l = ws + 32;
;   float m_reg = -1e30f, l_reg = 0; f32x16 o[4] = {}; bf16x8 qr[8];
;   const bf16_t* Qw = U.Q + (long)(wid * QBLK + r32) * LDP + hi * 8;
; #pragma unroll
;   for (int d0 = 0; d0 < 8; ++d0) qr[d0] = ld8(Qw + d0 * 16);
;   const int vb0 = (int)(uintptr_t)V_lds + v_rd_base(lane);
;   const int ka0 = (int)(uintptr_t)K_lds + KSWZ(r32, hi * 16);
;   unsigned koff[2], voff[2];
; #pragma unroll
;   for (int i = 0; i < 2; ++i) { const int ob = (2 * wid + i) * 1024 + lane * 16;
;     { const int row = ob >> 8, cpos = (ob >> 4) & 15, c = cpos ^ (row & 7); koff[i] = (unsigned)(row * LDP + c * 8); }
;     { const int st = ob >> 9, kk = (st >> 2) * 8 + ((ob >> 6) & 7), c = (st & 3) * 32 + ((ob >> 1) & 31), k = (kk & ~0xC) | ((kk & 4) << 1) | ((kk & 8) >> 1); voff[i] = (unsigned)(k * LDP + c); } }
;   typedef __attribute__((address_space(3))) unsigned lds_u32;
;   const int nsplit = U.nsplit, base1 = U.base1;
;     ...
;   const int NT = U.nt;
;   NDMA(0, 0); NPUB();
.LBB0_380:
	v_mov_b32_e32 v6, v210
	v_mov_b64_e32 v[2:3], s[58:59]
	v_readfirstlane_b32 s9, v6
	s_and_b32 s4, s9, 0x3fffffc0
	s_ashr_i32 s26, s9, 6
	s_lshl_b32 s4, s4, 2
	v_and_b32_e32 v140, 31, v6
	s_add_i32 s4, s4, 0
	s_lshl_b32 s66, s26, 5
	v_bfe_u32 v139, v6, 5, 1
	s_add_i32 s27, s4, 0x18000
	v_or_b32_e32 v0, s66, v140
	s_add_i32 s33, 0, 0x10000
	v_mad_i64_i32 v[2:3], s[4:5], v0, s96, v[2:3]
	v_lshlrev_b32_e32 v4, 4, v139
	v_mov_b32_e32 v5, v1
	s_cmp_lg_u32 s33, -1
	v_lshl_add_u64 v[2:3], v[2:3], 0, v[4:5]
	s_cselect_b32 s4, s33, 0
	s_lshl_b32 s29, s26, 11
	global_load_dwordx4 v[98:101], v[2:3], off
	global_load_dwordx4 v[102:105], v[2:3], off offset:32
	global_load_dwordx4 v[106:109], v[2:3], off offset:64
	global_load_dwordx4 v[110:113], v[2:3], off offset:96
	global_load_dwordx4 v[114:117], v[2:3], off offset:128
	global_load_dwordx4 v[118:121], v[2:3], off offset:160
	global_load_dwordx4 v[122:125], v[2:3], off offset:192
	global_load_dwordx4 v[126:129], v[2:3], off offset:224
	s_ashr_i32 s5, s29, 8
	v_lshrrev_b32_e32 v3, 1, v6
	v_bfe_u32 v0, v6, 2, 2
	s_and_b32 s26, s5, 0xfffff0
	v_and_b32_e32 v3, 8, v3
	v_and_b32_e32 v7, 63, v6
	s_lshr_b32 s5, s5, 1
	v_or3_b32 v0, v3, v0, s26
	v_lshlrev_b32_e32 v9, 4, v7
	v_and_or_b32 v0, s5, 4, v0
	v_mul_i32_i24_e32 v3, 0x1800, v0
	v_or_b32_e32 v0, s29, v9
	v_and_b32_e32 v2, 15, v6
	v_ashrrev_i32_e32 v0, 8, v0
	v_lshlrev_b32_e32 v5, 3, v7
	v_bitop3_b32 v10, v0, v2, 15 bitop3:0x6c
	v_mul_i32_i24_e32 v0, 0x1800, v0
	v_and_b32_e32 v8, 24, v5
	v_lshl_or_b32 v0, v10, 3, v0
	v_and_b32_e32 v10, 32, v6
	v_or3_b32 v130, v8, v10, v3
	v_or_b32_e32 v10, 0x400, v9
	v_or_b32_e32 v11, s29, v10
	v_ashrrev_i32_e32 v11, 8, v11
	v_bitop3_b32 v2, v11, v2, 15 bitop3:0x6c
	v_mul_i32_i24_e32 v11, 0x1800, v11
	v_lshl_or_b32 v132, v2, 3, v11
	v_lshrrev_b32_e32 v2, 4, v10
	s_cmp_lg_u32 0, -1
	v_and_b32_e32 v2, 0x60, v2
	s_cselect_b32 s26, 0, 0
	s_add_i32 s67, s33, s29
	v_or3_b32 v134, v8, v2, v3
	v_lshl_add_u64 v[2:3], v[0:1], 1, s[46:47]
	s_mov_b32 m0, s67
	v_mov_b32_e32 v131, v1
	s_add_i32 s30, s29, 0
	s_or_b32 s31, s29, 0x400
	global_load_lds_dwordx4 v[2:3], off
	v_lshl_add_u64 v[2:3], v[130:131], 1, s[22:23]
	s_mov_b32 m0, s30
	v_mov_b32_e32 v133, v1
	s_add_i32 s33, s33, s31
	global_load_lds_dwordx4 v[2:3], off
	v_lshl_add_u64 v[2:3], v[132:133], 1, s[46:47]
	s_mov_b32 m0, s33
	v_mov_b32_e32 v135, v1
	s_add_i32 s35, s30, 0x400
	global_load_lds_dwordx4 v[2:3], off
	v_lshl_add_u64 v[2:3], v[134:135], 1, s[22:23]
	s_mov_b32 m0, s35
	s_ashr_i32 s9, s9, 7
	global_load_lds_dwordx4 v[2:3], off
	v_lshlrev_b32_e32 v2, 1, v6
	v_and_b32_e32 v2, 32, v2
	v_and_or_b32 v2, v9, s97, v2
	v_and_b32_e32 v3, 0x100, v5
	v_bitop3_b32 v5, v139, v6, 15 bitop3:0x78
	v_or3_b32 v2, v2, v3, v8
	v_lshlrev_b32_e32 v3, 8, v140
	v_lshlrev_b32_e32 v5, 4, v5
	v_add_u32_e32 v142, s26, v2
	v_add3_u32 v143, v3, s4, v5
	v_and_or_b32 v3, s66, 32, v140
	s_add_i32 s26, s26, 0x8000
	v_add_u32_e32 v152, s26, v2
	v_lshl_or_b32 v2, v3, 8, v4
	v_mov_b32_e32 v3, v1
	s_add_i32 s9, s9, s3
	s_sub_i32 s26, s8, s24
	v_lshl_add_u64 v[136:137], s[6:7], 0, v[2:3]
	v_med3_i32 v2, s9, 4, v232
	s_sub_i32 s9, s26, s9
	s_add_i32 s6, s9, 7
	s_ashr_i32 s7, s6, 31
	s_lshl_b64 s[68:69], s[6:7], 12
	s_lshl_b32 s6, s24, 6
	s_waitcnt vmcnt(0)
	s_sub_i32 s8, s25, s6
	s_add_i32 s6, s9, 8
	v_mov_b32_e32 v16, v1
	v_mov_b32_e32 v17, v1
	v_cmp_gt_u32_e64 s[4:5], 32, v7
	v_lshl_add_u32 v146, v140, 2, s27
	v_add_u32_e32 v138, s27, v4
	v_readfirstlane_b32 s27, v2
	s_ashr_i32 s7, s6, 31
	v_mov_b32_e32 v2, v1
	v_mov_b32_e32 v4, v1
	v_mov_b32_e32 v5, v1
	v_mov_b32_e32 v6, v1
	v_mov_b32_e32 v7, v1
	v_mov_b32_e32 v8, v1
	v_mov_b32_e32 v9, v1
	v_mov_b32_e32 v10, v1
	v_mov_b32_e32 v11, v1
	v_mov_b32_e32 v12, v1
	v_mov_b32_e32 v13, v1
	v_mov_b32_e32 v14, v1
	v_mov_b32_e32 v15, v1
	v_mov_b64_e32 v[64:65], v[16:17]
	v_mov_b64_e32 v[48:49], v[16:17]
	v_mov_b64_e32 v[32:33], v[16:17]
	s_mov_b32 s90, 2
	v_lshlrev_b32_e32 v141, 2, v139
	v_xor_b32_e32 v144, 32, v143
	v_xor_b32_e32 v145, 64, v143
	v_xor_b32_e32 v147, 0x60, v143
	s_movk_i32 s91, 0x80
	v_xor_b32_e32 v148, 0x80, v143
	v_xor_b32_e32 v149, 0xa0, v143
	v_xor_b32_e32 v150, 0xc0, v143
	v_xor_b32_e32 v151, 0xe0, v143
	s_add_i32 s3, s27, -4
	s_add_i32 s27, s27, 4
	s_lshl_b64 s[80:81], s[6:7], 12
	v_mov_b32_e32 v153, 0
	v_mov_b32_e32 v155, 0xf149f2ca
	v_mov_b64_e32 v[62:63], v[14:15]
	v_mov_b64_e32 v[60:61], v[12:13]
	v_mov_b64_e32 v[58:59], v[10:11]
	v_mov_b64_e32 v[56:57], v[8:9]
	v_mov_b64_e32 v[54:55], v[6:7]
	v_mov_b64_e32 v[52:53], v[4:5]
	v_mov_b64_e32 v[50:51], v[2:3]
	v_mov_b64_e32 v[46:47], v[14:15]
	v_mov_b64_e32 v[44:45], v[12:13]
	v_mov_b64_e32 v[42:43], v[10:11]
	v_mov_b64_e32 v[40:41], v[8:9]
	v_mov_b64_e32 v[38:39], v[6:7]
	v_mov_b64_e32 v[36:37], v[4:5]
	v_mov_b64_e32 v[34:35], v[2:3]
	v_mov_b64_e32 v[30:31], v[14:15]
	v_mov_b64_e32 v[28:29], v[12:13]
	v_mov_b64_e32 v[26:27], v[10:11]
	v_mov_b64_e32 v[24:25], v[8:9]
	v_mov_b64_e32 v[22:23], v[6:7]
	v_mov_b64_e32 v[20:21], v[4:5]
	v_mov_b64_e32 v[18:19], v[2:3]
	s_waitcnt vmcnt(0) lgkmcnt(0)
	s_barrier
	s_branch .LBB0_383

; __device__ __forceinline__ int v_rd_base(int lane) { return ((lane & 3) << 3) | (((lane >> 2) & 3) << 6) | (((lane >> 4) & 1) << 5) | (((lane >> 5) & 1) << 8); }
; #define NPUB() do { asm volatile("s_waitcnt vmcnt(0)" ::: "memory"); __syncthreads(); } while (0)
; template <bool NA> __device__ __forceinline__ void unit_body_v128(const Unit& U, char* lds) {
;   int tid = threadIdx.x; asm volatile("" : "+v"(tid)); const int wid = __builtin_amdgcn_readfirstlane(tid >> 6), lane = tid & 63, r32 = lane & 31, hi = lane >> 5;
;   char* V_lds = lds; char* K_lds = lds + 2 * DA_VB;
;   float* ws = (float*)(lds + DA_WS_OFF) + wid * 64; float* li_l = ws; float* al_l = ws + 32;
;   float m_reg = -1e30f, l_reg = 0; f32x16 o[4] = {}; bf16x8 qr[8];
;   const bf16_t* Qw = U.Q + (long)(wid * QBLK + r32) * LDP + hi * 8;
; #pragma unroll
;   for (int d0 = 0; d0 < 8; ++d0) qr[d0] = ld8(Qw + d0 * 16);
;   const int vb0 = (int)(uintptr_t)V_lds + v_rd_base(lane);
;   const int ka0 = (int)(uintptr_t)K_lds + KSWZ(r32, hi * 16);
;   unsigned koff[2], voff[2];
; #pragma unroll
;   for (int i = 0; i < 2; ++i) { const int ob = (2 * wid + i) * 1024 + lane * 16;
;     { const int row = ob >> 8, cpos = (ob >> 4) & 15, c = cpos ^ (row & 7); koff[i] = (unsigned)(row * LDP + c * 8); }
;     { const int st = ob >> 9, kk = (st >> 2) * 8 + ((ob >> 6) & 7), c = (st & 3) * 32 + ((ob >> 1) & 31), k = (kk & ~0xC) | ((kk & 4) << 1) | ((kk & 8) >> 1); voff[i] = (unsigned)(k * LDP + c); } }
;   typedef __attribute__((address_space(3))) unsigned lds_u32;
;   const int nsplit = U.nsplit, base1 = U.base1;
;     ...
;   const int NT = U.nt;
;   NDMA(0, 0); NPUB();
.LBB0_405:
	s_cmp_lg_u32 s28, 0
	s_cbranch_scc0 .LBB0_426
	v_mov_b32_e32 v4, v210
	v_mov_b64_e32 v[2:3], s[58:59]
	v_readfirstlane_b32 s3, v4
	s_ashr_i32 s6, s3, 6
	s_and_b32 s3, s3, 0x3fffffc0
	s_lshl_b32 s3, s3, 2
	v_and_b32_e32 v139, 31, v4
	s_add_i32 s3, s3, 0
	s_lshl_b32 s66, s6, 5
	v_bfe_u32 v138, v4, 5, 1
	s_add_i32 s3, s3, 0x18000
	v_or_b32_e32 v0, s66, v139
	s_add_i32 s28, 0, 0x10000
	v_mad_i64_i32 v[2:3], s[4:5], v0, s96, v[2:3]
	v_lshlrev_b32_e32 v130, 4, v138
	v_mov_b32_e32 v131, v1
	s_cmp_lg_u32 s28, -1
	v_lshl_add_u64 v[2:3], v[2:3], 0, v[130:131]
	s_cselect_b32 s4, s28, 0
	s_lshl_b32 s8, s6, 11
	global_load_dwordx4 v[98:101], v[2:3], off
	global_load_dwordx4 v[102:105], v[2:3], off offset:32
	global_load_dwordx4 v[106:109], v[2:3], off offset:64
	global_load_dwordx4 v[110:113], v[2:3], off offset:96
	global_load_dwordx4 v[114:117], v[2:3], off offset:128
	global_load_dwordx4 v[118:121], v[2:3], off offset:160
	global_load_dwordx4 v[122:125], v[2:3], off offset:192
	global_load_dwordx4 v[126:129], v[2:3], off offset:224
	s_ashr_i32 s5, s8, 8
	v_lshrrev_b32_e32 v3, 1, v4
	v_bfe_u32 v0, v4, 2, 2
	s_and_b32 s6, s5, 0xfffff0
	v_and_b32_e32 v3, 8, v3
	v_and_b32_e32 v5, 63, v4
	s_lshr_b32 s5, s5, 1
	v_or3_b32 v0, v3, v0, s6
	v_lshlrev_b32_e32 v8, 4, v5
	v_and_or_b32 v0, s5, 4, v0
	v_mul_i32_i24_e32 v3, 0x1800, v0
	v_or_b32_e32 v0, s8, v8
	v_and_b32_e32 v2, 15, v4
	v_ashrrev_i32_e32 v0, 8, v0
	v_lshlrev_b32_e32 v6, 3, v5
	v_bitop3_b32 v9, v0, v2, 15 bitop3:0x6c
	v_mul_i32_i24_e32 v0, 0x1800, v0
	v_and_b32_e32 v7, 24, v6
	v_lshl_or_b32 v0, v9, 3, v0
	v_and_b32_e32 v9, 32, v4
	v_or3_b32 v132, v7, v9, v3
	v_or_b32_e32 v9, 0x400, v8
	v_or_b32_e32 v10, s8, v9
	v_ashrrev_i32_e32 v10, 8, v10
	v_bitop3_b32 v2, v10, v2, 15 bitop3:0x6c
	v_mul_i32_i24_e32 v10, 0x1800, v10
	v_lshl_or_b32 v134, v2, 3, v10
	v_lshrrev_b32_e32 v2, 4, v9
	s_cmp_lg_u32 0, -1
	v_and_b32_e32 v2, 0x60, v2
	s_cselect_b32 s6, 0, 0
	s_add_i32 s9, s28, s8
	v_or3_b32 v136, v7, v2, v3
	v_lshl_add_u64 v[2:3], v[0:1], 1, s[46:47]
	s_mov_b32 m0, s9
	v_mov_b32_e32 v133, v1
	s_add_i32 s26, s8, 0
	s_or_b32 s27, s8, 0x400
	global_load_lds_dwordx4 v[2:3], off
	v_lshl_add_u64 v[2:3], v[132:133], 1, s[22:23]
	s_mov_b32 m0, s26
	v_mov_b32_e32 v135, v1
	s_add_i32 s28, s28, s27
	global_load_lds_dwordx4 v[2:3], off
	v_lshl_add_u64 v[2:3], v[134:135], 1, s[46:47]
	s_mov_b32 m0, s28
	v_mov_b32_e32 v137, v1
	s_add_i32 s29, s26, 0x400
	global_load_lds_dwordx4 v[2:3], off
	v_lshl_add_u64 v[2:3], v[136:137], 1, s[22:23]
	s_mov_b32 m0, s29
	v_mov_b32_e32 v16, v1
	global_load_lds_dwordx4 v[2:3], off
	v_lshlrev_b32_e32 v2, 1, v4
	v_and_b32_e32 v2, 32, v2
	v_and_or_b32 v2, v8, s97, v2
	v_and_b32_e32 v3, 0x100, v6
	v_or3_b32 v2, v2, v3, v7
	v_bitop3_b32 v4, v138, v4, 15 bitop3:0x78
	v_lshlrev_b32_e32 v3, 8, v139
	v_add_u32_e32 v131, s6, v2
	v_lshlrev_b32_e32 v4, 4, v4
	s_waitcnt vmcnt(0)
	s_add_i32 s6, s6, 0x8000
	v_mov_b32_e32 v17, v1
	v_add3_u32 v140, v3, s4, v4
	v_cmp_gt_u32_e64 s[4:5], 32, v5
	v_add_u32_e32 v149, s6, v2
	s_lshl_b32 s6, s24, 6
	v_mov_b32_e32 v2, v1
	v_mov_b32_e32 v3, v1
	v_mov_b32_e32 v4, v1
	v_mov_b32_e32 v5, v1
	v_mov_b32_e32 v6, v1
	v_mov_b32_e32 v7, v1
	v_mov_b32_e32 v8, v1
	v_mov_b32_e32 v9, v1
	v_mov_b32_e32 v10, v1
	v_mov_b32_e32 v11, v1
	v_mov_b32_e32 v12, v1
	v_mov_b32_e32 v13, v1
	v_mov_b32_e32 v14, v1
	v_mov_b32_e32 v15, v1
	v_mov_b64_e32 v[64:65], v[16:17]
	v_mov_b64_e32 v[48:49], v[16:17]
	v_mov_b64_e32 v[32:33], v[16:17]
	s_mov_b32 s30, 2
	v_xor_b32_e32 v141, 32, v140
	v_xor_b32_e32 v142, 64, v140
	v_xor_b32_e32 v144, 0x60, v140
	s_movk_i32 s31, 0x80
	v_xor_b32_e32 v145, 0x80, v140
	v_xor_b32_e32 v146, 0xa0, v140
	v_xor_b32_e32 v147, 0xc0, v140
	v_xor_b32_e32 v148, 0xe0, v140
	v_lshl_add_u32 v143, v139, 2, s3
	s_sub_i32 s25, s25, s6
	v_mov_b32_e32 v150, 0
	v_mov_b32_e32 v152, 0xf149f2ca
	v_mov_b64_e32 v[62:63], v[14:15]
	v_mov_b64_e32 v[60:61], v[12:13]
	v_mov_b64_e32 v[58:59], v[10:11]
	v_mov_b64_e32 v[56:57], v[8:9]
	v_mov_b64_e32 v[54:55], v[6:7]
	v_mov_b64_e32 v[52:53], v[4:5]
	v_mov_b64_e32 v[50:51], v[2:3]
	v_mov_b64_e32 v[46:47], v[14:15]
	v_mov_b64_e32 v[44:45], v[12:13]
	v_mov_b64_e32 v[42:43], v[10:11]
	v_mov_b64_e32 v[40:41], v[8:9]
	v_mov_b64_e32 v[38:39], v[6:7]
	v_mov_b64_e32 v[36:37], v[4:5]
	v_mov_b64_e32 v[34:35], v[2:3]
	v_mov_b64_e32 v[30:31], v[14:15]
	v_mov_b64_e32 v[28:29], v[12:13]
	v_mov_b64_e32 v[26:27], v[10:11]
	v_mov_b64_e32 v[24:25], v[8:9]
	v_mov_b64_e32 v[22:23], v[6:7]
	v_mov_b64_e32 v[20:21], v[4:5]
	v_mov_b64_e32 v[18:19], v[2:3]
	s_waitcnt vmcnt(0) lgkmcnt(0)
	s_barrier
	s_branch .LBB0_409

; __device__ __forceinline__ int v_rd_base(int lane) { return ((lane & 3) << 3) | (((lane >> 2) & 3) << 6) | (((lane >> 4) & 1) << 5) | (((lane >> 5) & 1) << 8); }
; #define DPUB() do { asm volatile("s_waitcnt vmcnt(0)" ::: "memory"); __syncthreads(); } while (0)
; __device__ __forceinline__ void unit_body_da(const Unit& U, char* lds) {
;   int tid = threadIdx.x; asm volatile("" : "+v"(tid)); const int wid = __builtin_amdgcn_readfirstlane(tid >> 6), lane = tid & 63, r32 = lane & 31, hi = lane >> 5;
;   char* V_lds = lds; char* K_lds = lds + 2 * DA_VB;
;   float* ws = (float*)(lds + DA_WS_OFF) + wid * 64; float* li_l = ws; float* al_l = ws + 32;
;   float m_reg = -1e30f, l_reg = 0; f32x16 o[8] = {}; bf16x8 qr[8];
;   const bf16_t* Qw = U.Q + (long)(wid * QBLK + r32) * LDP + hi * 8;
; #pragma unroll
;   for (int d0 = 0; d0 < 8; ++d0) qr[d0] = ld8(Qw + d0 * 16);
;   const int vb0 = (int)(uintptr_t)V_lds + v_rd_base(lane);
;   const int ka0 = (int)(uintptr_t)K_lds + KSWZ(r32, hi * 16);
;   constexpr float C = SCALE * 1.4426950408889634f;
;   unsigned koff[2], voff[2][2];
; #pragma unroll
;   for (int i = 0; i < 2; ++i) { const int ob = (2 * wid + i) * 1024 + lane * 16;
;     { const int row = ob >> 8, cpos = (ob >> 4) & 15, c = cpos ^ (row & 7); koff[i] = (unsigned)(row * LDP + c * 8); }
;     { const int st = ob >> 9, kk = (st >> 2) * 8 + ((ob >> 6) & 7), c = (st & 3) * 32 + ((ob >> 1) & 31), k = (kk & ~0xC) | ((kk & 4) << 1) | ((kk & 8) >> 1);
;       voff[0][i] = (unsigned)(k * LDP + c); voff[1][i] = (unsigned)(k * LDP + 128 + c); } }
;   typedef __attribute__((address_space(3))) unsigned lds_u32;
;     ...
;   const int NT = U.nt;
;   DDMA(0, 0); DPUB();
.LBB0_426:
	s_cbranch_execz .LBB0_370
	v_mov_b32_e32 v8, v210
	v_mov_b64_e32 v[2:3], s[58:59]
	v_readfirstlane_b32 s3, v8
	s_ashr_i32 s6, s3, 6
	s_and_b32 s3, s3, 0x3fffffc0
	s_lshl_b32 s3, s3, 2
	v_and_b32_e32 v234, 31, v8
	s_add_i32 s24, s3, 0
	s_lshl_b32 s64, s6, 5
	v_bfe_u32 v233, v8, 5, 1
	s_add_i32 s24, s24, 0x18000
	v_or_b32_e32 v0, s64, v234
	s_add_i32 s67, 0, 0x10000
	v_mad_i64_i32 v[2:3], s[4:5], v0, s96, v[2:3]
	v_lshlrev_b32_e32 v212, 4, v233
	v_mov_b32_e32 v213, v1
	s_cmp_lg_u32 s67, -1
	v_lshl_add_u64 v[2:3], v[2:3], 0, v[212:213]
	s_cselect_b32 s3, s67, 0
	s_lshl_b32 s25, s6, 11
	global_load_dwordx4 v[162:165], v[2:3], off
	global_load_dwordx4 v[166:169], v[2:3], off offset:32
	global_load_dwordx4 v[170:173], v[2:3], off offset:64
	global_load_dwordx4 v[174:177], v[2:3], off offset:96
	global_load_dwordx4 v[178:181], v[2:3], off offset:128
	global_load_dwordx4 v[182:185], v[2:3], off offset:160
	global_load_dwordx4 v[186:189], v[2:3], off offset:192
	global_load_dwordx4 v[190:193], v[2:3], off offset:224
	s_ashr_i32 s4, s25, 8
	v_lshrrev_b32_e32 v2, 1, v8
	v_and_b32_e32 v9, 63, v8
	v_bfe_u32 v0, v8, 2, 2
	s_and_b32 s5, s4, 0xfffff0
	v_and_b32_e32 v2, 8, v2
	v_lshlrev_b32_e32 v12, 4, v9
	s_lshr_b32 s4, s4, 1
	v_or3_b32 v0, v2, v0, s5
	v_and_or_b32 v0, s4, 4, v0
	v_or_b32_e32 v5, 0x400, v12
	v_mul_i32_i24_e32 v13, 0x1800, v0
	v_or_b32_e32 v0, s25, v12
	v_or_b32_e32 v4, s25, v5
	v_and_b32_e32 v3, 15, v8
	v_ashrrev_i32_e32 v0, 8, v0
	v_ashrrev_i32_e32 v4, 8, v4
	v_bitop3_b32 v2, v0, v3, 15 bitop3:0x6c
	v_bitop3_b32 v3, v4, v3, 15 bitop3:0x6c
	v_mul_i32_i24_e32 v4, 0x1800, v4
	v_lshlrev_b32_e32 v10, 3, v9
	v_mul_i32_i24_e32 v0, 0x1800, v0
	v_lshl_or_b32 v4, v3, 3, v4
	v_lshrrev_b32_e32 v3, 4, v5
	v_and_b32_e32 v11, 24, v10
	v_lshl_or_b32 v0, v2, 3, v0
	v_and_b32_e32 v14, 32, v8
	v_and_b32_e32 v3, 0x60, v3
	s_add_i32 s28, s67, s25
	v_or3_b32 v2, v11, v14, v13
	v_or3_b32 v6, v11, v3, v13
	v_lshl_add_u64 v[214:215], v[0:1], 1, s[46:47]
	s_mov_b32 m0, s28
	v_mov_b32_e32 v3, v1
	s_add_i32 s29, s25, 0
	global_load_lds_dwordx4 v[214:215], off
	v_lshl_add_u64 v[2:3], v[2:3], 1, s[22:23]
	s_mov_b32 m0, s29
	s_mov_b64 s[4:5], 0x100
	s_add_i32 s65, s29, 0x4000
	s_or_b32 s66, s25, 0x400
	global_load_lds_dwordx4 v[2:3], off
	v_lshl_add_u64 v[2:3], v[2:3], 0, s[4:5]
	s_mov_b32 m0, s65
	v_mov_b32_e32 v5, v1
	s_add_i32 s67, s67, s66
	global_load_lds_dwordx4 v[2:3], off
	v_lshl_add_u64 v[216:217], v[4:5], 1, s[46:47]
	s_mov_b32 m0, s67
	v_mov_b32_e32 v7, v1
	s_add_i32 s68, s29, 0x400
	global_load_lds_dwordx4 v[216:217], off
	v_lshl_add_u64 v[2:3], v[6:7], 1, s[22:23]
	s_mov_b32 m0, s68
	s_add_i32 s69, s29, 0x4400
	global_load_lds_dwordx4 v[2:3], off
	v_lshl_add_u64 v[2:3], v[2:3], 0, s[4:5]
	s_mov_b32 m0, s69
	v_lshlrev_b32_e32 v0, 1, v8
	global_load_lds_dwordx4 v[2:3], off
	v_and_b32_e32 v0, 32, v0
	v_and_or_b32 v0, v12, s97, v0
	v_and_b32_e32 v2, 0x100, v10
	s_cmp_lg_u32 0, -1
	v_or3_b32 v0, v0, v2, v11
	v_bitop3_b32 v3, v233, v8, 15 bitop3:0x78
	s_cselect_b32 s6, 0, 0
	v_lshlrev_b32_e32 v2, 8, v234
	v_lshlrev_b32_e32 v3, 4, v3
	v_add_u32_e32 v213, s6, v0
	s_add_i32 s6, s6, 0x8000
	v_add3_u32 v235, v2, s3, v3
	v_add_u32_e32 v244, s6, v0
	v_or3_b32 v0, v13, v14, v11
	s_movk_i32 s3, 0x60
	v_lshl_add_u64 v[218:219], v[0:1], 1, s[22:23]
	v_bitop3_b32 v0, v9, s3, 64 bitop3:0xc8
	v_or3_b32 v0, v13, v0, v11
	v_mov_b32_e32 v14, v1
	v_mov_b32_e32 v15, v1
	s_waitcnt vmcnt(0)
	v_cmp_gt_u32_e64 s[4:5], 32, v9
	v_lshl_add_u64 v[220:221], v[0:1], 1, s[22:23]
	v_mov_b32_e32 v0, v1
	v_mov_b32_e32 v2, v1
	v_mov_b32_e32 v3, v1
	v_mov_b32_e32 v4, v1
	v_mov_b32_e32 v6, v1
	v_mov_b32_e32 v8, v1
	v_mov_b32_e32 v9, v1
	v_mov_b32_e32 v10, v1
	v_mov_b32_e32 v11, v1
	v_mov_b32_e32 v12, v1
	v_mov_b32_e32 v13, v1
	v_mov_b64_e32 v[128:129], v[14:15]
	v_mov_b64_e32 v[112:113], v[14:15]
	v_mov_b64_e32 v[96:97], v[14:15]
	v_mov_b64_e32 v[80:81], v[14:15]
	v_mov_b64_e32 v[64:65], v[14:15]
	v_mov_b64_e32 v[48:49], v[14:15]
	v_mov_b64_e32 v[32:33], v[14:15]
	v_mov_b64_e32 v[126:127], v[12:13]
	v_mov_b64_e32 v[124:125], v[10:11]
	v_mov_b64_e32 v[122:123], v[8:9]
	v_mov_b64_e32 v[120:121], v[6:7]
	v_mov_b64_e32 v[118:119], v[4:5]
	v_mov_b64_e32 v[116:117], v[2:3]
	v_mov_b64_e32 v[114:115], v[0:1]
	v_mov_b64_e32 v[110:111], v[12:13]
	v_mov_b64_e32 v[108:109], v[10:11]
	v_mov_b64_e32 v[106:107], v[8:9]
	v_mov_b64_e32 v[104:105], v[6:7]
	v_mov_b64_e32 v[102:103], v[4:5]
	v_mov_b64_e32 v[100:101], v[2:3]
	v_mov_b64_e32 v[98:99], v[0:1]
	v_mov_b64_e32 v[94:95], v[12:13]
	v_mov_b64_e32 v[92:93], v[10:11]
	v_mov_b64_e32 v[90:91], v[8:9]
	v_mov_b64_e32 v[88:89], v[6:7]
	v_mov_b64_e32 v[86:87], v[4:5]
	v_mov_b64_e32 v[84:85], v[2:3]
	v_mov_b64_e32 v[82:83], v[0:1]
	v_mov_b64_e32 v[78:79], v[12:13]
	v_mov_b64_e32 v[76:77], v[10:11]
	v_mov_b64_e32 v[74:75], v[8:9]
	v_mov_b64_e32 v[72:73], v[6:7]
	v_mov_b64_e32 v[70:71], v[4:5]
	v_mov_b64_e32 v[68:69], v[2:3]
	v_mov_b64_e32 v[66:67], v[0:1]
	v_mov_b64_e32 v[62:63], v[12:13]
	v_mov_b64_e32 v[60:61], v[10:11]
	v_mov_b64_e32 v[58:59], v[8:9]
	v_mov_b64_e32 v[56:57], v[6:7]
	v_mov_b64_e32 v[54:55], v[4:5]
	v_mov_b64_e32 v[52:53], v[2:3]
	v_mov_b64_e32 v[50:51], v[0:1]
	v_mov_b64_e32 v[46:47], v[12:13]
	v_mov_b64_e32 v[44:45], v[10:11]
	v_mov_b64_e32 v[42:43], v[8:9]
	v_mov_b64_e32 v[40:41], v[6:7]
	v_mov_b64_e32 v[38:39], v[4:5]
	v_mov_b64_e32 v[36:37], v[2:3]
	v_mov_b64_e32 v[34:35], v[0:1]
	v_mov_b64_e32 v[30:31], v[12:13]
	v_mov_b64_e32 v[28:29], v[10:11]
	v_mov_b64_e32 v[26:27], v[8:9]
	v_mov_b64_e32 v[24:25], v[6:7]
	v_mov_b64_e32 v[22:23], v[4:5]
	v_mov_b64_e32 v[20:21], v[2:3]
	v_mov_b64_e32 v[18:19], v[0:1]
	v_mov_b64_e32 v[16:17], v[14:15]
	s_mov_b32 s80, 2
	v_xor_b32_e32 v236, 32, v235
	v_xor_b32_e32 v238, 64, v235
	v_xor_b32_e32 v239, 0x60, v235
	v_xor_b32_e32 v240, 0x80, v235
	v_xor_b32_e32 v241, 0xa0, v235
	v_xor_b32_e32 v242, 0xc0, v235
	v_xor_b32_e32 v243, 0xe0, v235
	v_lshl_add_u32 v237, v234, 2, s24
	v_mov_b32_e32 v245, 0
	v_mov_b32_e32 v246, 0xf149f2ca
	s_mov_b64 s[22:23], 0
	v_mov_b64_e32 v[14:15], v[12:13]
	v_mov_b64_e32 v[12:13], v[10:11]
	v_mov_b64_e32 v[10:11], v[8:9]
	v_mov_b64_e32 v[8:9], v[6:7]
	v_mov_b64_e32 v[6:7], v[4:5]
	v_mov_b64_e32 v[4:5], v[2:3]
	v_mov_b64_e32 v[2:3], v[0:1]
	s_waitcnt vmcnt(0) lgkmcnt(0)
	s_barrier
	s_branch .LBB0_430

; __device__ __forceinline__ int v_rd_base(int lane) { return ((lane & 3) << 3) | (((lane >> 2) & 3) << 6) | (((lane >> 4) & 1) << 5) | (((lane >> 5) & 1) << 8); }
; #define NPUB() do { asm volatile("s_waitcnt vmcnt(0)" ::: "memory"); __syncthreads(); } while (0)
; template <bool NA> __device__ __forceinline__ void unit_body_v128(const Unit& U, char* lds) {
;   int tid = threadIdx.x; asm volatile("" : "+v"(tid)); const int wid = __builtin_amdgcn_readfirstlane(tid >> 6), lane = tid & 63, r32 = lane & 31, hi = lane >> 5;
;   char* V_lds = lds; char* K_lds = lds + 2 * DA_VB;
;   float* ws = (float*)(lds + DA_WS_OFF) + wid * 64; float* li_l = ws; float* al_l = ws + 32;
;   float m_reg = -1e30f, l_reg = 0; f32x16 o[4] = {}; bf16x8 qr[8];
;   const bf16_t* Qw = U.Q + (long)(wid * QBLK + r32) * LDP + hi * 8;
; #pragma unroll
;   for (int d0 = 0; d0 < 8; ++d0) qr[d0] = ld8(Qw + d0 * 16);
;   const int vb0 = (int)(uintptr_t)V_lds + v_rd_base(lane);
;   const int ka0 = (int)(uintptr_t)K_lds + KSWZ(r32, hi * 16);
;   unsigned koff[2], voff[2];
; #pragma unroll
;   for (int i = 0; i < 2; ++i) { const int ob = (2 * wid + i) * 1024 + lane * 16;
;     { const int row = ob >> 8, cpos = (ob >> 4) & 15, c = cpos ^ (row & 7); koff[i] = (unsigned)(row * LDP + c * 8); }
;     { const int st = ob >> 9, kk = (st >> 2) * 8 + ((ob >> 6) & 7), c = (st & 3) * 32 + ((ob >> 1) & 31), k = (kk & ~0xC) | ((kk & 4) << 1) | ((kk & 8) >> 1); voff[i] = (unsigned)(k * LDP + c); } }
;   typedef __attribute__((address_space(3))) unsigned lds_u32;
;   const int nsplit = U.nsplit, base1 = U.base1;
;     ...
;   const int NT = U.nt;
;   NDMA(0, 0); NPUB();
.LBB0_1410:
	v_mov_b32_e32 v6, v210
	v_mov_b64_e32 v[2:3], s[56:57]
	v_readfirstlane_b32 s5, v6
	s_and_b32 s0, s5, 0x3fffffc0
	s_ashr_i32 s4, s5, 6
	s_lshl_b32 s0, s0, 2
	v_and_b32_e32 v140, 31, v6
	s_add_i32 s0, s0, 0
	s_lshl_b32 s62, s4, 5
	s_waitcnt vmcnt(0)
	v_bfe_u32 v139, v6, 5, 1
	s_add_i32 s27, s0, 0x18000
	v_or_b32_e32 v0, s62, v140
	s_add_i32 s97, 0, 0x10000
	v_mad_i64_i32 v[2:3], s[0:1], v0, s92, v[2:3]
	v_lshlrev_b32_e32 v4, 4, v139
	v_mov_b32_e32 v5, v1
	s_cmp_lg_u32 s97, -1
	v_lshl_add_u64 v[2:3], v[2:3], 0, v[4:5]
	s_cselect_b32 s0, s97, 0
	s_lshl_b32 s29, s4, 11
	global_load_dwordx4 v[98:101], v[2:3], off
	global_load_dwordx4 v[102:105], v[2:3], off offset:32
	global_load_dwordx4 v[106:109], v[2:3], off offset:64
	global_load_dwordx4 v[110:113], v[2:3], off offset:96
	global_load_dwordx4 v[114:117], v[2:3], off offset:128
	global_load_dwordx4 v[118:121], v[2:3], off offset:160
	global_load_dwordx4 v[122:125], v[2:3], off offset:192
	global_load_dwordx4 v[126:129], v[2:3], off offset:224
	s_ashr_i32 s1, s29, 8
	v_lshrrev_b32_e32 v3, 1, v6
	v_bfe_u32 v0, v6, 2, 2
	s_and_b32 s4, s1, 0xfffff0
	v_and_b32_e32 v3, 8, v3
	v_and_b32_e32 v7, 63, v6
	s_lshr_b32 s1, s1, 1
	v_or3_b32 v0, v3, v0, s4
	v_lshlrev_b32_e32 v9, 4, v7
	v_and_or_b32 v0, s1, 4, v0
	v_mul_i32_i24_e32 v3, 0x1800, v0
	v_or_b32_e32 v0, s29, v9
	v_and_b32_e32 v2, 15, v6
	v_ashrrev_i32_e32 v0, 8, v0
	v_lshlrev_b32_e32 v5, 3, v7
	v_bitop3_b32 v10, v0, v2, 15 bitop3:0x6c
	v_mul_i32_i24_e32 v0, 0x1800, v0
	v_and_b32_e32 v8, 24, v5
	v_lshl_or_b32 v0, v10, 3, v0
	v_and_b32_e32 v10, 32, v6
	v_or3_b32 v130, v8, v10, v3
	v_or_b32_e32 v10, 0x400, v9
	v_or_b32_e32 v11, s29, v10
	v_ashrrev_i32_e32 v11, 8, v11
	v_bitop3_b32 v2, v11, v2, 15 bitop3:0x6c
	v_mul_i32_i24_e32 v11, 0x1800, v11
	v_lshl_or_b32 v132, v2, 3, v11
	v_lshrrev_b32_e32 v2, 4, v10
	s_cmp_lg_u32 0, -1
	v_and_b32_e32 v2, 0x60, v2
	s_cselect_b32 s59, 0, 0
	s_add_i32 s63, s97, s29
	v_or3_b32 v134, v8, v2, v3
	v_lshl_add_u64 v[2:3], v[0:1], 1, s[24:25]
	s_mov_b32 m0, s63
	v_mov_b32_e32 v131, v1
	s_add_i32 s30, s29, 0
	s_or_b32 s31, s29, 0x400
	global_load_lds_dwordx4 v[2:3], off
	v_lshl_add_u64 v[2:3], v[130:131], 1, s[22:23]
	s_mov_b32 m0, s30
	v_mov_b32_e32 v133, v1
	s_add_i32 s97, s97, s31
	global_load_lds_dwordx4 v[2:3], off
	v_lshl_add_u64 v[2:3], v[132:133], 1, s[24:25]
	s_mov_b32 m0, s97
	v_mov_b32_e32 v135, v1
	s_add_i32 s21, s30, 0x400
	global_load_lds_dwordx4 v[2:3], off
	v_lshl_add_u64 v[2:3], v[134:135], 1, s[22:23]
	s_mov_b32 m0, s21
	s_ashr_i32 s66, s5, 7
	global_load_lds_dwordx4 v[2:3], off
	v_lshlrev_b32_e32 v2, 1, v6
	v_and_b32_e32 v2, 32, v2
	v_and_or_b32 v2, v9, s93, v2
	v_and_b32_e32 v3, 0x100, v5
	v_bitop3_b32 v5, v139, v6, 15 bitop3:0x78
	v_or3_b32 v2, v2, v3, v8
	v_lshlrev_b32_e32 v3, 8, v140
	v_lshlrev_b32_e32 v5, 4, v5
	v_add_u32_e32 v142, s59, v2
	v_add3_u32 v143, v3, s0, v5
	v_and_or_b32 v3, s62, 32, v140
	s_add_i32 s59, s59, 0x8000
	s_add_i32 s66, s66, s3
	s_sub_i32 s26, s26, s28
	v_add_u32_e32 v152, s59, v2
	v_lshl_or_b32 v2, v3, 8, v4
	v_mov_b32_e32 v3, v1
	s_sub_i32 s68, s26, s66
	v_lshl_add_u64 v[136:137], s[6:7], 0, v[2:3]
	s_add_i32 s6, s68, 7
	s_ashr_i32 s7, s6, 31
	v_med3_i32 v2, s66, 4, v232
	s_lshl_b64 s[66:67], s[6:7], 12
	s_lshl_b32 s6, s28, 6
	s_waitcnt vmcnt(0)
	s_sub_i32 s59, s58, s6
	s_add_i32 s6, s68, 8
	v_mov_b32_e32 v16, v1
	v_mov_b32_e32 v17, v1
	v_cmp_gt_u32_e64 s[0:1], 32, v7
	v_lshl_add_u32 v146, v140, 2, s27
	v_add_u32_e32 v138, s27, v4
	v_readfirstlane_b32 s27, v2
	s_ashr_i32 s7, s6, 31
	v_mov_b32_e32 v2, v1
	v_mov_b32_e32 v4, v1
	v_mov_b32_e32 v5, v1
	v_mov_b32_e32 v6, v1
	v_mov_b32_e32 v7, v1
	v_mov_b32_e32 v8, v1
	v_mov_b32_e32 v9, v1
	v_mov_b32_e32 v10, v1
	v_mov_b32_e32 v11, v1
	v_mov_b32_e32 v12, v1
	v_mov_b32_e32 v13, v1
	v_mov_b32_e32 v14, v1
	v_mov_b32_e32 v15, v1
	v_mov_b64_e32 v[64:65], v[16:17]
	v_mov_b64_e32 v[48:49], v[16:17]
	v_mov_b64_e32 v[32:33], v[16:17]
	s_mov_b32 s4, 2
	v_lshlrev_b32_e32 v141, 2, v139
	v_xor_b32_e32 v144, 32, v143
	v_xor_b32_e32 v145, 64, v143
	v_xor_b32_e32 v147, 0x60, v143
	s_movk_i32 s5, 0x80
	v_xor_b32_e32 v148, 0x80, v143
	v_xor_b32_e32 v149, 0xa0, v143
	v_xor_b32_e32 v150, 0xc0, v143
	v_xor_b32_e32 v151, 0xe0, v143
	s_add_i32 s3, s27, -4
	s_add_i32 s27, s27, 4
	s_lshl_b64 s[68:69], s[6:7], 12
	v_mov_b32_e32 v153, 0
	v_mov_b32_e32 v155, 0xf149f2ca
	v_mov_b64_e32 v[62:63], v[14:15]
	v_mov_b64_e32 v[60:61], v[12:13]
	v_mov_b64_e32 v[58:59], v[10:11]
	v_mov_b64_e32 v[56:57], v[8:9]
	v_mov_b64_e32 v[54:55], v[6:7]
	v_mov_b64_e32 v[52:53], v[4:5]
	v_mov_b64_e32 v[50:51], v[2:3]
	v_mov_b64_e32 v[46:47], v[14:15]
	v_mov_b64_e32 v[44:45], v[12:13]
	v_mov_b64_e32 v[42:43], v[10:11]
	v_mov_b64_e32 v[40:41], v[8:9]
	v_mov_b64_e32 v[38:39], v[6:7]
	v_mov_b64_e32 v[36:37], v[4:5]
	v_mov_b64_e32 v[34:35], v[2:3]
	v_mov_b64_e32 v[30:31], v[14:15]
	v_mov_b64_e32 v[28:29], v[12:13]
	v_mov_b64_e32 v[26:27], v[10:11]
	v_mov_b64_e32 v[24:25], v[8:9]
	v_mov_b64_e32 v[22:23], v[6:7]
	v_mov_b64_e32 v[20:21], v[4:5]
	v_mov_b64_e32 v[18:19], v[2:3]
	s_waitcnt vmcnt(0) lgkmcnt(0)
	s_barrier
	s_branch .LBB0_1413

; __device__ __forceinline__ int v_rd_base(int lane) { return ((lane & 3) << 3) | (((lane >> 2) & 3) << 6) | (((lane >> 4) & 1) << 5) | (((lane >> 5) & 1) << 8); }
; #define DPUB() do { asm volatile("s_waitcnt vmcnt(0)" ::: "memory"); __syncthreads(); } while (0)
; __device__ __forceinline__ void unit_body_da(const Unit& U, char* lds) {
;   int tid = threadIdx.x; asm volatile("" : "+v"(tid)); const int wid = __builtin_amdgcn_readfirstlane(tid >> 6), lane = tid & 63, r32 = lane & 31, hi = lane >> 5;
;   char* V_lds = lds; char* K_lds = lds + 2 * DA_VB;
;   float* ws = (float*)(lds + DA_WS_OFF) + wid * 64; float* li_l = ws; float* al_l = ws + 32;
;   float m_reg = -1e30f, l_reg = 0; f32x16 o[8] = {}; bf16x8 qr[8];
;   const bf16_t* Qw = U.Q + (long)(wid * QBLK + r32) * LDP + hi * 8;
; #pragma unroll
;   for (int d0 = 0; d0 < 8; ++d0) qr[d0] = ld8(Qw + d0 * 16);
;   const int vb0 = (int)(uintptr_t)V_lds + v_rd_base(lane);
;   const int ka0 = (int)(uintptr_t)K_lds + KSWZ(r32, hi * 16);
;   constexpr float C = SCALE * 1.4426950408889634f;
;   unsigned koff[2], voff[2][2];
; #pragma unroll
;   for (int i = 0; i < 2; ++i) { const int ob = (2 * wid + i) * 1024 + lane * 16;
;     { const int row = ob >> 8, cpos = (ob >> 4) & 15, c = cpos ^ (row & 7); koff[i] = (unsigned)(row * LDP + c * 8); }
;     { const int st = ob >> 9, kk = (st >> 2) * 8 + ((ob >> 6) & 7), c = (st & 3) * 32 + ((ob >> 1) & 31), k = (kk & ~0xC) | ((kk & 4) << 1) | ((kk & 8) >> 1);
;       voff[0][i] = (unsigned)(k * LDP + c); voff[1][i] = (unsigned)(k * LDP + 128 + c); } }
;   typedef __attribute__((address_space(3))) unsigned lds_u32;
;     ...
;   const int NT = U.nt;
;   DDMA(0, 0); DPUB();
.LBB0_1432:
	s_and_b64 vcc, exec, s[62:63]
	s_cbranch_vccz .LBB0_1404
	v_mov_b32_e32 v8, v210
	v_mov_b64_e32 v[2:3], s[56:57]
	v_readfirstlane_b32 s0, v8
	s_ashr_i32 s3, s0, 6
	s_and_b32 s0, s0, 0x3fffffc0
	s_lshl_b32 s0, s0, 2
	v_and_b32_e32 v234, 31, v8
	s_add_i32 s28, s0, 0
	s_lshl_b32 s60, s3, 5
	v_bfe_u32 v233, v8, 5, 1
	s_add_i32 s28, s28, 0x18000
	v_or_b32_e32 v0, s60, v234
	s_add_i32 s67, 0, 0x10000
	v_mad_i64_i32 v[2:3], s[0:1], v0, s92, v[2:3]
	v_lshlrev_b32_e32 v212, 4, v233
	v_mov_b32_e32 v213, v1
	s_cmp_lg_u32 s67, -1
	v_lshl_add_u64 v[2:3], v[2:3], 0, v[212:213]
	s_cselect_b32 s0, s67, 0
	s_lshl_b32 s29, s3, 11
	global_load_dwordx4 v[162:165], v[2:3], off
	global_load_dwordx4 v[166:169], v[2:3], off offset:32
	global_load_dwordx4 v[170:173], v[2:3], off offset:64
	global_load_dwordx4 v[174:177], v[2:3], off offset:96
	global_load_dwordx4 v[178:181], v[2:3], off offset:128
	global_load_dwordx4 v[182:185], v[2:3], off offset:160
	global_load_dwordx4 v[186:189], v[2:3], off offset:192
	global_load_dwordx4 v[190:193], v[2:3], off offset:224
	s_ashr_i32 s1, s29, 8
	v_lshrrev_b32_e32 v2, 1, v8
	v_and_b32_e32 v9, 63, v8
	v_bfe_u32 v0, v8, 2, 2
	s_and_b32 s3, s1, 0xfffff0
	v_and_b32_e32 v2, 8, v2
	s_waitcnt vmcnt(0)
	v_lshlrev_b32_e32 v12, 4, v9
	s_lshr_b32 s1, s1, 1
	v_or3_b32 v0, v2, v0, s3
	v_and_or_b32 v0, s1, 4, v0
	v_or_b32_e32 v5, 0x400, v12
	v_mul_i32_i24_e32 v13, 0x1800, v0
	v_or_b32_e32 v0, s29, v12
	v_or_b32_e32 v4, s29, v5
	v_and_b32_e32 v3, 15, v8
	v_ashrrev_i32_e32 v0, 8, v0
	v_ashrrev_i32_e32 v4, 8, v4
	v_bitop3_b32 v2, v0, v3, 15 bitop3:0x6c
	v_bitop3_b32 v3, v4, v3, 15 bitop3:0x6c
	v_mul_i32_i24_e32 v4, 0x1800, v4
	v_lshlrev_b32_e32 v10, 3, v9
	v_mul_i32_i24_e32 v0, 0x1800, v0
	v_lshl_or_b32 v4, v3, 3, v4
	v_lshrrev_b32_e32 v3, 4, v5
	v_and_b32_e32 v11, 24, v10
	v_lshl_or_b32 v0, v2, 3, v0
	v_and_b32_e32 v14, 32, v8
	v_and_b32_e32 v3, 0x60, v3
	s_add_i32 s61, s67, s29
	v_or3_b32 v2, v11, v14, v13
	v_or3_b32 v6, v11, v3, v13
	v_lshl_add_u64 v[214:215], v[0:1], 1, s[24:25]
	s_mov_b32 m0, s61
	v_mov_b32_e32 v3, v1
	s_add_i32 s62, s29, 0
	global_load_lds_dwordx4 v[214:215], off
	v_lshl_add_u64 v[2:3], v[2:3], 1, s[22:23]
	s_mov_b32 m0, s62
	s_add_i32 s63, s62, 0x4000
	s_or_b32 s66, s29, 0x400
	global_load_lds_dwordx4 v[2:3], off
	v_lshl_add_u64 v[2:3], v[2:3], 0, s[8:9]
	s_mov_b32 m0, s63
	v_mov_b32_e32 v5, v1
	s_add_i32 s67, s67, s66
	global_load_lds_dwordx4 v[2:3], off
	v_lshl_add_u64 v[216:217], v[4:5], 1, s[24:25]
	s_mov_b32 m0, s67
	v_mov_b32_e32 v7, v1
	s_add_i32 s68, s62, 0x400
	global_load_lds_dwordx4 v[216:217], off
	v_lshl_add_u64 v[2:3], v[6:7], 1, s[22:23]
	s_mov_b32 m0, s68
	s_add_i32 s69, s62, 0x4400
	global_load_lds_dwordx4 v[2:3], off
	v_lshl_add_u64 v[2:3], v[2:3], 0, s[8:9]
	s_mov_b32 m0, s69
	v_lshlrev_b32_e32 v0, 1, v8
	global_load_lds_dwordx4 v[2:3], off
	v_and_b32_e32 v0, 32, v0
	v_and_or_b32 v0, v12, s93, v0
	v_and_b32_e32 v2, 0x100, v10
	s_cmp_lg_u32 0, -1
	v_or3_b32 v0, v0, v2, v11
	s_cselect_b32 s3, 0, 0
	v_add_u32_e32 v213, s3, v0
	s_add_i32 s3, s3, 0x8000
	v_add_u32_e32 v244, s3, v0
	v_or3_b32 v0, v13, v14, v11
	s_movk_i32 s3, 0x60
	v_bitop3_b32 v3, v233, v8, 15 bitop3:0x78
	v_lshl_add_u64 v[218:219], v[0:1], 1, s[22:23]
	v_bitop3_b32 v0, v9, s3, 64 bitop3:0xc8
	v_lshlrev_b32_e32 v2, 8, v234
	v_lshlrev_b32_e32 v3, 4, v3
	v_or3_b32 v0, v13, v0, v11
	v_mov_b32_e32 v14, v1
	v_mov_b32_e32 v15, v1
	v_add3_u32 v235, v2, s0, v3
	s_waitcnt vmcnt(0)
	v_cmp_gt_u32_e64 s[0:1], 32, v9
	v_lshl_add_u64 v[220:221], v[0:1], 1, s[22:23]
	v_mov_b32_e32 v0, v1
	v_mov_b32_e32 v2, v1
	v_mov_b32_e32 v3, v1
	v_mov_b32_e32 v4, v1
	v_mov_b32_e32 v6, v1
	v_mov_b32_e32 v8, v1
	v_mov_b32_e32 v9, v1
	v_mov_b32_e32 v10, v1
	v_mov_b32_e32 v11, v1
	v_mov_b32_e32 v12, v1
	v_mov_b32_e32 v13, v1
	v_mov_b64_e32 v[128:129], v[14:15]
	v_mov_b64_e32 v[112:113], v[14:15]
	v_mov_b64_e32 v[96:97], v[14:15]
	v_mov_b64_e32 v[80:81], v[14:15]
	v_mov_b64_e32 v[64:65], v[14:15]
	v_mov_b64_e32 v[48:49], v[14:15]
	v_mov_b64_e32 v[32:33], v[14:15]
	v_mov_b64_e32 v[126:127], v[12:13]
	v_mov_b64_e32 v[124:125], v[10:11]
	v_mov_b64_e32 v[122:123], v[8:9]
	v_mov_b64_e32 v[120:121], v[6:7]
	v_mov_b64_e32 v[118:119], v[4:5]
	v_mov_b64_e32 v[116:117], v[2:3]
	v_mov_b64_e32 v[114:115], v[0:1]
	v_mov_b64_e32 v[110:111], v[12:13]
	v_mov_b64_e32 v[108:109], v[10:11]
	v_mov_b64_e32 v[106:107], v[8:9]
	v_mov_b64_e32 v[104:105], v[6:7]
	v_mov_b64_e32 v[102:103], v[4:5]
	v_mov_b64_e32 v[100:101], v[2:3]
	v_mov_b64_e32 v[98:99], v[0:1]
	v_mov_b64_e32 v[94:95], v[12:13]
	v_mov_b64_e32 v[92:93], v[10:11]
	v_mov_b64_e32 v[90:91], v[8:9]
	v_mov_b64_e32 v[88:89], v[6:7]
	v_mov_b64_e32 v[86:87], v[4:5]
	v_mov_b64_e32 v[84:85], v[2:3]
	v_mov_b64_e32 v[82:83], v[0:1]
	v_mov_b64_e32 v[78:79], v[12:13]
	v_mov_b64_e32 v[76:77], v[10:11]
	v_mov_b64_e32 v[74:75], v[8:9]
	v_mov_b64_e32 v[72:73], v[6:7]
	v_mov_b64_e32 v[70:71], v[4:5]
	v_mov_b64_e32 v[68:69], v[2:3]
	v_mov_b64_e32 v[66:67], v[0:1]
	v_mov_b64_e32 v[62:63], v[12:13]
	v_mov_b64_e32 v[60:61], v[10:11]
	v_mov_b64_e32 v[58:59], v[8:9]
	v_mov_b64_e32 v[56:57], v[6:7]
	v_mov_b64_e32 v[54:55], v[4:5]
	v_mov_b64_e32 v[52:53], v[2:3]
	v_mov_b64_e32 v[50:51], v[0:1]
	v_mov_b64_e32 v[46:47], v[12:13]
	v_mov_b64_e32 v[44:45], v[10:11]
	v_mov_b64_e32 v[42:43], v[8:9]
	v_mov_b64_e32 v[40:41], v[6:7]
	v_mov_b64_e32 v[38:39], v[4:5]
	v_mov_b64_e32 v[36:37], v[2:3]
	v_mov_b64_e32 v[34:35], v[0:1]
	v_mov_b64_e32 v[30:31], v[12:13]
	v_mov_b64_e32 v[28:29], v[10:11]
	v_mov_b64_e32 v[26:27], v[8:9]
	v_mov_b64_e32 v[24:25], v[6:7]
	v_mov_b64_e32 v[22:23], v[4:5]
	v_mov_b64_e32 v[20:21], v[2:3]
	v_mov_b64_e32 v[18:19], v[0:1]
	v_mov_b64_e32 v[16:17], v[14:15]
	s_mov_b32 s80, 2
	v_xor_b32_e32 v236, 32, v235
	v_xor_b32_e32 v238, 64, v235
	v_xor_b32_e32 v239, 0x60, v235
	v_xor_b32_e32 v240, 0x80, v235
	v_xor_b32_e32 v241, 0xa0, v235
	v_xor_b32_e32 v242, 0xc0, v235
	v_xor_b32_e32 v243, 0xe0, v235
	v_lshl_add_u32 v237, v234, 2, s28
	v_mov_b32_e32 v245, 0
	v_mov_b32_e32 v246, 0xf149f2ca
	s_mov_b64 s[22:23], 0
	v_mov_b64_e32 v[14:15], v[12:13]
	v_mov_b64_e32 v[12:13], v[10:11]
	v_mov_b64_e32 v[10:11], v[8:9]
	v_mov_b64_e32 v[8:9], v[6:7]
	v_mov_b64_e32 v[6:7], v[4:5]
	v_mov_b64_e32 v[4:5], v[2:3]
	v_mov_b64_e32 v[2:3], v[0:1]
	s_waitcnt vmcnt(0) lgkmcnt(0)
	s_barrier
	s_branch .LBB0_1436
